# v36 + stick-breaking tile loop: 14x (4 v_mov + v_pk_mul_f32) -> 2 v_mul_f32 and 22x self-product v_pk_mul_f32 with dead high half -> v_mul_f32 (bit-identical multiplies, ~21 fewer VALU issues per key
# speedup vs baseline: 1.0044x; 1.0044x over previous
; template <int MODE, bool SAMPLE>
; __device__ __forceinline__ void unit(LAS char* lds, const UnitDesc& D) {
;     ...
;             float glo[8], ghi[8];
; #pragma unroll
;             for (int g = 0; g < 4; ++g) { swap32((s0[4 * g] * s0[4 * g + 1]) * (s0[4 * g + 2] * s0[4 * g + 3]), glo[g], ghi[g]);
;                                           swap32((s1[4 * g] * s1[4 * g + 1]) * (s1[4 * g + 2] * s1[4 * g + 3]), glo[4 + g], ghi[4 + g]); }
;             float T = R;
; #pragma unroll
;             for (int m = 7; m >= 0; --m) {
;                 float run = hi ? T : T * ghi[m];
;                 if (m < 4) {
; #pragma unroll
;                     for (int e = 3; e >= 0; --e) { const float a = p0[4 * m + e] * run; run *= s0[4 * m + e]; p0[4 * m + e] = a; }
;                 } else {
; #pragma unroll
;                     for (int e = 3; e >= 0; --e) { const float a = p1[4 * (m - 4) + e] * run; run *= s1[4 * (m - 4) + e]; p1[4 * (m - 4) + e] = a; }
;                 }
;                 T *= glo[m] * ghi[m];
;             }
;             R = T;
;             wdone = __all(R == 0.f);
;         }
;         pack_p(p0, p1, pa0, pa1, pa2, pa3);
.LBB0_1626:
	v_mul_f32_e32 v236, v79, v78
	v_mul_f32_e32 v237, v174, v175
	v_mul_f32_e32 v238, v177, v176
	v_mul_f32_e32 v239, v186, v187
	v_mul_f32_e32 v226, v71, v70
	v_mul_f32_e32 v227, v72, v73
	v_mul_f32_e32 v238, v238, v239
	v_mul_f32_e32 v228, v87, v86
	v_mul_f32_e32 v229, v88, v89
	v_mov_b32_e32 v78, v238
	v_mul_f32_e32 v230, v75, v74
	v_mul_f32_e32 v231, v76, v77
	v_permlane32_swap_b32_e32 v238, v78
	v_mul_f32_e32 v232, v91, v90
	v_mul_f32_e32 v233, v168, v169
	v_mul_f32_e32 v86, v216, v78
	v_mul_f32_e32 v232, v232, v233
	v_cndmask_b32_e64 v86, v216, v86, s[10:11]
	v_mov_b32_e32 v234, v232
	v_mul_f32_e32 v201, v201, v86
	v_mul_f32_e32 v86, v187, v86
	v_permlane32_swap_b32_e32 v232, v234
	v_mul_f32_e32 v187, v200, v86
	v_mul_f32_e32 v86, v186, v86
	v_mul_f32_e32 v235, v238, v78
	v_mov_b32_e32 v233, v216
	v_mul_f32_e32 v186, v199, v86
	v_mul_f32_e32 v86, v177, v86
	v_pk_mul_f32 v[176:177], v[232:233], v[234:235]
	v_mul_f32_e32 v228, v228, v229
	v_mul_f32_e32 v78, v177, v234
	v_cndmask_b32_e64 v78, v177, v78, s[10:11]
	v_mul_f32_e32 v197, v197, v78
	v_mul_f32_e32 v78, v169, v78
	v_mov_b32_e32 v70, v228
	v_mul_f32_e32 v169, v196, v78
	v_mul_f32_e32 v78, v168, v78
	v_permlane32_swap_b32_e32 v228, v70
	v_mul_f32_e32 v168, v195, v78
	v_mul_f32_e32 v78, v91, v78
	v_mul_f32_e32 v90, v176, v177
	v_mul_f32_e32 v222, v83, v82
	v_mul_f32_e32 v223, v84, v85
	v_mul_f32_e32 v194, v194, v78
	v_mul_f32_e32 v78, v90, v70
	v_mul_f32_e32 v222, v222, v223
	v_cndmask_b32_e64 v78, v90, v78, s[10:11]
	v_mov_b32_e32 v224, v222
	v_mul_f32_e32 v91, v193, v78
	v_mul_f32_e32 v78, v89, v78
	v_permlane32_swap_b32_e32 v222, v224
	v_mul_f32_e32 v89, v192, v78
	v_mul_f32_e32 v78, v88, v78
	v_mul_f32_e32 v223, v228, v70
	v_mov_b32_e32 v225, v90
	v_mul_f32_e32 v198, v198, v86
	v_mul_f32_e32 v88, v191, v78
	v_mul_f32_e32 v78, v87, v78
	v_pk_mul_f32 v[86:87], v[222:223], v[224:225]
	v_mul_f32_e32 v236, v236, v237
	v_mul_f32_e32 v70, v87, v224
	v_cndmask_b32_e64 v70, v87, v70, s[10:11]
	v_mul_f32_e32 v90, v189, v70
	v_mul_f32_e32 v70, v85, v70
	v_mov_b32_e32 v74, v236
	v_mul_f32_e32 v177, v188, v70
	v_mul_f32_e32 v70, v84, v70
	v_permlane32_swap_b32_e32 v236, v74
	v_mul_f32_e32 v185, v185, v70
	v_mul_f32_e32 v70, v83, v70
	v_mul_f32_e32 v84, v86, v87
	v_mul_f32_e32 v184, v184, v70
	v_mul_f32_e32 v70, v84, v74
	v_mul_f32_e32 v230, v230, v231
	v_cndmask_b32_e64 v70, v84, v70, s[10:11]
	v_mov_b32_e32 v82, v230
	v_mul_f32_e32 v85, v183, v70
	v_mul_f32_e32 v70, v175, v70
	v_permlane32_swap_b32_e32 v230, v82
	v_mul_f32_e32 v86, v182, v70
	v_mul_f32_e32 v70, v174, v70
	v_mul_f32_e32 v231, v236, v74
	v_mov_b32_e32 v83, v84
	v_mul_f32_e32 v176, v190, v78
	v_mul_f32_e32 v87, v181, v70
	v_mul_f32_e32 v70, v79, v70
	v_pk_mul_f32 v[78:79], v[230:231], v[82:83]
	v_mul_f32_e32 v174, v180, v70
	v_mul_f32_e32 v70, v79, v82
	v_cndmask_b32_e64 v70, v79, v70, s[10:11]
	v_mul_f32_e32 v226, v226, v227
	v_mul_f32_e32 v81, v81, v70
	v_mul_f32_e32 v70, v77, v70
	v_mov_b32_e32 v220, v66
	v_mov_b32_e32 v66, v226
	v_mul_f32_e32 v77, v80, v70
	v_mul_f32_e32 v70, v76, v70
	v_permlane32_swap_b32_e32 v226, v66
	v_mul_f32_e32 v76, v173, v70
	v_mul_f32_e32 v70, v75, v70
	v_mul_f32_e32 v74, v78, v79
	v_mov_b32_e32 v218, v67
	v_mov_b32_e32 v219, v68
	v_mov_b32_e32 v221, v69
	v_mul_f32_e32 v80, v172, v70
	v_mul_f32_e32 v70, v74, v66
	v_pk_mul_f32 v[218:219], v[218:219], v[220:221]
	v_cndmask_b32_e64 v70, v74, v70, s[10:11]
	v_mul_f32_e32 v218, v218, v219
	v_mul_f32_e32 v75, v171, v70
	v_mul_f32_e32 v70, v73, v70
	v_mov_b32_e32 v220, v218
	v_mul_f32_e32 v73, v170, v70
	v_mul_f32_e32 v70, v72, v70
	v_permlane32_swap_b32_e32 v218, v220
	v_mul_f32_e32 v72, v97, v70
	v_mul_f32_e32 v70, v71, v70
	v_mul_f32_e32 v219, v226, v66
	v_mov_b32_e32 v221, v74
	v_mul_f32_e32 v78, v96, v70
	v_pk_mul_f32 v[70:71], v[218:219], v[220:221]
	v_add_u32_e32 v217, s2, v214
	v_mul_f32_e32 v66, v71, v220
	v_cndmask_b32_e64 v66, v71, v66, s[10:11]
	v_mul_f32_e32 v216, v70, v71
	v_mul_f32_e32 v69, v69, v66
	v_cmp_eq_f32_e32 vcc, 0, v216
	v_mul_f32_e32 v68, v68, v69
	s_cmp_eq_u64 vcc, exec
	v_mul_f32_e32 v67, v67, v68
	v_mul_f32_e32 v74, v95, v66
	v_mul_f32_e32 v69, v94, v69
	v_mul_f32_e32 v68, v93, v68
	s_cselect_b64 s[14:15], -1, 0
	v_mul_f32_e32 v67, v92, v67
	v_cndmask_b32_e64 v66, 0, 1, s[14:15]
	v_cvt_pk_bf16_f32 v68, v67, v68
	v_cvt_pk_bf16_f32 v69, v69, v74
	v_cvt_pk_bf16_f32 v70, v78, v72
	v_cvt_pk_bf16_f32 v71, v73, v75
	v_cvt_pk_bf16_f32 v72, v80, v76
	v_cvt_pk_bf16_f32 v73, v77, v81
	v_cvt_pk_bf16_f32 v74, v174, v87
	v_cvt_pk_bf16_f32 v75, v86, v85
	v_cvt_pk_bf16_f32 v76, v184, v185
	v_cvt_pk_bf16_f32 v77, v177, v90
	v_cvt_pk_bf16_f32 v78, v176, v88
	v_cvt_pk_bf16_f32 v79, v89, v91
	v_cvt_pk_bf16_f32 v80, v194, v168
	v_cvt_pk_bf16_f32 v81, v169, v197
	v_cvt_pk_bf16_f32 v82, v198, v186
	v_cvt_pk_bf16_f32 v83, v187, v201
	s_nop 0
	v_permlane32_swap_b32_e32 v68, v70
	v_permlane32_swap_b32_e32 v69, v71
	v_permlane32_swap_b32_e32 v72, v74
	v_permlane32_swap_b32_e32 v73, v75
	v_permlane32_swap_b32_e32 v76, v78
	v_permlane32_swap_b32_e32 v77, v79
	v_permlane32_swap_b32_e32 v80, v82
	v_permlane32_swap_b32_e32 v81, v83
	ds_read_b64_tr_b16 v[84:85], v217 offset:0
	ds_read_b64_tr_b16 v[86:87], v217 offset:0x800
	ds_read_b64_tr_b16 v[88:89], v217 offset:0x1000
	ds_read_b64_tr_b16 v[90:91], v217 offset:0x1800
	ds_read_b64_tr_b16 v[92:93], v217 offset:0x2000
	ds_read_b64_tr_b16 v[94:95], v217 offset:0x2800
	ds_read_b64_tr_b16 v[168:169], v217 offset:0x3000
	ds_read_b64_tr_b16 v[170:171], v217 offset:0x3800
	s_waitcnt lgkmcnt(0)
; __device__ __forceinline__ void pv_tile(f32x16* o, unsigned vb0, bf16x8 pa0, bf16x8 pa1, bf16x8 pa2, bf16x8 pa3) {
;     ...
;     PV_D0(0); PV_D0(1); PV_D0(2); PV_D0(3);
	s_nop 0
	v_mfma_f32_32x32x16_bf16 v[50:65], v[68:71], v[84:87], v[50:65]
	ds_read_b64_tr_b16 v[84:85], v217 offset:0x200
	ds_read_b64_tr_b16 v[86:87], v217 offset:0xa00
	v_mfma_f32_32x32x16_bf16 v[50:65], v[72:75], v[88:91], v[50:65]
	ds_read_b64_tr_b16 v[88:89], v217 offset:0x1200
	ds_read_b64_tr_b16 v[90:91], v217 offset:0x1a00
	v_mfma_f32_32x32x16_bf16 v[50:65], v[76:79], v[92:95], v[50:65]
	ds_read_b64_tr_b16 v[92:93], v217 offset:0x2200
	ds_read_b64_tr_b16 v[94:95], v217 offset:0x2a00
	ds_read_b64_tr_b16 v[172:173], v217 offset:0x3200
	ds_read_b64_tr_b16 v[174:175], v217 offset:0x3a00
	s_waitcnt lgkmcnt(0)
	v_mfma_f32_32x32x16_bf16 v[50:65], v[80:83], v[168:171], v[50:65]
	v_mfma_f32_32x32x16_bf16 v[34:49], v[68:71], v[84:87], v[34:49]
	ds_read_b64_tr_b16 v[84:85], v217 offset:0x400
	ds_read_b64_tr_b16 v[86:87], v217 offset:0xc00
	v_mfma_f32_32x32x16_bf16 v[34:49], v[72:75], v[88:91], v[34:49]
	ds_read_b64_tr_b16 v[88:89], v217 offset:0x1400
	ds_read_b64_tr_b16 v[90:91], v217 offset:0x1c00
	v_mfma_f32_32x32x16_bf16 v[34:49], v[76:79], v[92:95], v[34:49]
	ds_read_b64_tr_b16 v[92:93], v217 offset:0x2400
	ds_read_b64_tr_b16 v[94:95], v217 offset:0x2c00
	ds_read_b64_tr_b16 v[168:169], v217 offset:0x3400
	ds_read_b64_tr_b16 v[170:171], v217 offset:0x3c00
	s_waitcnt lgkmcnt(0)
	v_mfma_f32_32x32x16_bf16 v[34:49], v[80:83], v[172:175], v[34:49]
	v_mfma_f32_32x32x16_bf16 v[18:33], v[68:71], v[84:87], v[18:33]
	ds_read_b64_tr_b16 v[84:85], v217 offset:0x600
	ds_read_b64_tr_b16 v[86:87], v217 offset:0xe00
	v_mfma_f32_32x32x16_bf16 v[18:33], v[72:75], v[88:91], v[18:33]
	ds_read_b64_tr_b16 v[88:89], v217 offset:0x1600
	ds_read_b64_tr_b16 v[90:91], v217 offset:0x1e00
	v_mfma_f32_32x32x16_bf16 v[18:33], v[76:79], v[92:95], v[18:33]
	ds_read_b64_tr_b16 v[92:93], v217 offset:0x2600
	ds_read_b64_tr_b16 v[94:95], v217 offset:0x2e00
	ds_read_b64_tr_b16 v[172:173], v217 offset:0x3600
	ds_read_b64_tr_b16 v[174:175], v217 offset:0x3e00
	s_waitcnt lgkmcnt(0)
	v_mfma_f32_32x32x16_bf16 v[18:33], v[80:83], v[168:171], v[18:33]
	v_mfma_f32_32x32x16_bf16 v[2:17], v[68:71], v[84:87], v[2:17]
	v_mfma_f32_32x32x16_bf16 v[2:17], v[72:75], v[88:91], v[2:17]
	v_mfma_f32_32x32x16_bf16 v[2:17], v[76:79], v[92:95], v[2:17]
	v_mfma_f32_32x32x16_bf16 v[2:17], v[80:83], v[172:175], v[2:17]

; template <int MODE, bool SAMPLE>
; __device__ __forceinline__ void unit(LAS char* lds, const UnitDesc& D) {
;     ...
;             float glo[8], ghi[8];
; #pragma unroll
;             for (int g = 0; g < 4; ++g) { swap32((s0[4 * g] * s0[4 * g + 1]) * (s0[4 * g + 2] * s0[4 * g + 3]), glo[g], ghi[g]);
;                                           swap32((s1[4 * g] * s1[4 * g + 1]) * (s1[4 * g + 2] * s1[4 * g + 3]), glo[4 + g], ghi[4 + g]); }
;             float T = R;
; #pragma unroll
;             for (int m = 7; m >= 0; --m) {
;                 float run = hi ? T : T * ghi[m];
;                 if (m < 4) {
; #pragma unroll
;                     for (int e = 3; e >= 0; --e) { const float a = p0[4 * m + e] * run; run *= s0[4 * m + e]; p0[4 * m + e] = a; }
;                 } else {
; #pragma unroll
;                     for (int e = 3; e >= 0; --e) { const float a = p1[4 * (m - 4) + e] * run; run *= s1[4 * (m - 4) + e]; p1[4 * (m - 4) + e] = a; }
;                 }
;                 T *= glo[m] * ghi[m];
;             }
;             R = T;
;             wdone = __all(R == 0.f);
;         }
;         pack_p(p0, p1, pa0, pa1, pa2, pa3);
.LBB0_1773:
	v_mul_f32_e32 v224, v79, v78
	v_mul_f32_e32 v225, v160, v161
	v_mul_f32_e32 v226, v165, v164
	v_mul_f32_e32 v227, v172, v173
	v_mul_f32_e32 v214, v71, v70
	v_mul_f32_e32 v215, v72, v73
	v_mul_f32_e32 v226, v226, v227
	v_mul_f32_e32 v216, v87, v86
	v_mul_f32_e32 v217, v88, v89
	v_mov_b32_e32 v78, v226
	v_mul_f32_e32 v218, v75, v74
	v_mul_f32_e32 v219, v76, v77
	v_permlane32_swap_b32_e32 v226, v78
	v_mul_f32_e32 v220, v91, v90
	v_mul_f32_e32 v221, v154, v155
	v_mul_f32_e32 v86, v204, v78
	v_mul_f32_e32 v220, v220, v221
	v_cndmask_b32_e64 v86, v204, v86, s[10:11]
	v_mov_b32_e32 v222, v220
	v_mul_f32_e32 v189, v189, v86
	v_mul_f32_e32 v86, v173, v86
	v_permlane32_swap_b32_e32 v220, v222
	v_mul_f32_e32 v173, v188, v86
	v_mul_f32_e32 v86, v172, v86
	v_mul_f32_e32 v223, v226, v78
	v_mov_b32_e32 v221, v204
	v_mul_f32_e32 v172, v187, v86
	v_mul_f32_e32 v86, v165, v86
	v_pk_mul_f32 v[164:165], v[220:221], v[222:223]
	v_mul_f32_e32 v216, v216, v217
	v_mul_f32_e32 v78, v165, v222
	v_cndmask_b32_e64 v78, v165, v78, s[10:11]
	v_mul_f32_e32 v185, v185, v78
	v_mul_f32_e32 v78, v155, v78
	v_mov_b32_e32 v70, v216
	v_mul_f32_e32 v155, v184, v78
	v_mul_f32_e32 v78, v154, v78
	v_permlane32_swap_b32_e32 v216, v70
	v_mul_f32_e32 v154, v183, v78
	v_mul_f32_e32 v78, v91, v78
	v_mul_f32_e32 v90, v164, v165
	v_mul_f32_e32 v210, v83, v82
	v_mul_f32_e32 v211, v84, v85
	v_mul_f32_e32 v182, v182, v78
	v_mul_f32_e32 v78, v90, v70
	v_mul_f32_e32 v210, v210, v211
	v_cndmask_b32_e64 v78, v90, v78, s[10:11]
	v_mov_b32_e32 v212, v210
	v_mul_f32_e32 v91, v181, v78
	v_mul_f32_e32 v78, v89, v78
	v_permlane32_swap_b32_e32 v210, v212
	v_mul_f32_e32 v89, v180, v78
	v_mul_f32_e32 v78, v88, v78
	v_mul_f32_e32 v211, v216, v70
	v_mov_b32_e32 v213, v90
	v_mul_f32_e32 v186, v186, v86
	v_mul_f32_e32 v88, v177, v78
	v_mul_f32_e32 v78, v87, v78
	v_pk_mul_f32 v[86:87], v[210:211], v[212:213]
	v_mul_f32_e32 v224, v224, v225
	v_mul_f32_e32 v70, v87, v212
	v_cndmask_b32_e64 v70, v87, v70, s[10:11]
	v_mul_f32_e32 v90, v175, v70
	v_mul_f32_e32 v70, v85, v70
	v_mov_b32_e32 v74, v224
	v_mul_f32_e32 v165, v174, v70
	v_mul_f32_e32 v70, v84, v70
	v_permlane32_swap_b32_e32 v224, v74
	v_mul_f32_e32 v171, v171, v70
	v_mul_f32_e32 v70, v83, v70
	v_mul_f32_e32 v84, v86, v87
	v_mul_f32_e32 v170, v170, v70
	v_mul_f32_e32 v70, v84, v74
	v_mul_f32_e32 v218, v218, v219
	v_cndmask_b32_e64 v70, v84, v70, s[10:11]
	v_mov_b32_e32 v82, v218
	v_mul_f32_e32 v85, v169, v70
	v_mul_f32_e32 v70, v161, v70
	v_permlane32_swap_b32_e32 v218, v82
	v_mul_f32_e32 v86, v168, v70
	v_mul_f32_e32 v70, v160, v70
	v_mul_f32_e32 v219, v224, v74
	v_mov_b32_e32 v83, v84
	v_mul_f32_e32 v164, v176, v78
	v_mul_f32_e32 v87, v167, v70
	v_mul_f32_e32 v70, v79, v70
	v_pk_mul_f32 v[78:79], v[218:219], v[82:83]
	v_mul_f32_e32 v160, v166, v70
	v_mul_f32_e32 v70, v79, v82
	v_cndmask_b32_e64 v70, v79, v70, s[10:11]
	v_mul_f32_e32 v214, v214, v215
	v_mul_f32_e32 v81, v81, v70
	v_mul_f32_e32 v70, v77, v70
	v_mov_b32_e32 v208, v66
	v_mov_b32_e32 v66, v214
	v_mul_f32_e32 v77, v80, v70
	v_mul_f32_e32 v70, v76, v70
	v_permlane32_swap_b32_e32 v214, v66
	v_mul_f32_e32 v76, v159, v70
	v_mul_f32_e32 v70, v75, v70
	v_mul_f32_e32 v74, v78, v79
	v_mov_b32_e32 v206, v67
	v_mov_b32_e32 v207, v68
	v_mov_b32_e32 v209, v69
	v_mul_f32_e32 v80, v158, v70
	v_mul_f32_e32 v70, v74, v66
	v_pk_mul_f32 v[206:207], v[206:207], v[208:209]
	v_cndmask_b32_e64 v70, v74, v70, s[10:11]
	v_mul_f32_e32 v206, v206, v207
	v_mul_f32_e32 v75, v157, v70
	v_mul_f32_e32 v70, v73, v70
	v_mov_b32_e32 v208, v206
	v_mul_f32_e32 v73, v156, v70
	v_mul_f32_e32 v70, v72, v70
	v_permlane32_swap_b32_e32 v206, v208
	v_mul_f32_e32 v72, v97, v70
	v_mul_f32_e32 v70, v71, v70
	v_mul_f32_e32 v207, v214, v66
	v_mov_b32_e32 v209, v74
	v_mul_f32_e32 v78, v96, v70
	v_pk_mul_f32 v[70:71], v[206:207], v[208:209]
	v_add_u32_e32 v205, s91, v201
	v_mul_f32_e32 v66, v71, v208
	v_cndmask_b32_e64 v66, v71, v66, s[10:11]
	v_mul_f32_e32 v204, v70, v71
	v_mul_f32_e32 v69, v69, v66
	v_cmp_eq_f32_e32 vcc, 0, v204
	v_mul_f32_e32 v68, v68, v69
	s_cmp_eq_u64 vcc, exec
	v_mul_f32_e32 v67, v67, v68
	v_mul_f32_e32 v74, v95, v66
	v_mul_f32_e32 v69, v94, v69
	v_mul_f32_e32 v68, v93, v68
	s_cselect_b64 s[14:15], -1, 0
	v_mul_f32_e32 v67, v92, v67
	v_cndmask_b32_e64 v66, 0, 1, s[14:15]
	v_cvt_pk_bf16_f32 v68, v67, v68
	v_cvt_pk_bf16_f32 v69, v69, v74
	v_cvt_pk_bf16_f32 v70, v78, v72
	v_cvt_pk_bf16_f32 v71, v73, v75
	v_cvt_pk_bf16_f32 v72, v80, v76
	v_cvt_pk_bf16_f32 v73, v77, v81
	v_cvt_pk_bf16_f32 v74, v160, v87
	v_cvt_pk_bf16_f32 v75, v86, v85
	v_cvt_pk_bf16_f32 v76, v170, v171
	v_cvt_pk_bf16_f32 v77, v165, v90
	v_cvt_pk_bf16_f32 v78, v164, v88
	v_cvt_pk_bf16_f32 v79, v89, v91
	v_cvt_pk_bf16_f32 v80, v182, v154
	v_cvt_pk_bf16_f32 v81, v155, v185
	v_cvt_pk_bf16_f32 v82, v186, v172
	v_cvt_pk_bf16_f32 v83, v173, v189
	s_nop 0
	v_permlane32_swap_b32_e32 v68, v70
	v_permlane32_swap_b32_e32 v69, v71
	v_permlane32_swap_b32_e32 v72, v74
	v_permlane32_swap_b32_e32 v73, v75
	v_permlane32_swap_b32_e32 v76, v78
	v_permlane32_swap_b32_e32 v77, v79
	v_permlane32_swap_b32_e32 v80, v82
	v_permlane32_swap_b32_e32 v81, v83
	ds_read_b64_tr_b16 v[84:85], v205 offset:0
	ds_read_b64_tr_b16 v[86:87], v205 offset:0x800
	ds_read_b64_tr_b16 v[88:89], v205 offset:0x1000
	ds_read_b64_tr_b16 v[90:91], v205 offset:0x1800
	ds_read_b64_tr_b16 v[92:93], v205 offset:0x2000
	ds_read_b64_tr_b16 v[94:95], v205 offset:0x2800
	ds_read_b64_tr_b16 v[154:155], v205 offset:0x3000
	ds_read_b64_tr_b16 v[156:157], v205 offset:0x3800
	s_waitcnt lgkmcnt(0)
; __device__ __forceinline__ void pv_tile(f32x16* o, unsigned vb0, bf16x8 pa0, bf16x8 pa1, bf16x8 pa2, bf16x8 pa3) {
;     ...
;     PV_D0(0); PV_D0(1); PV_D0(2); PV_D0(3);
	s_nop 0
	v_mfma_f32_32x32x16_bf16 v[50:65], v[68:71], v[84:87], v[50:65]
	ds_read_b64_tr_b16 v[84:85], v205 offset:0x200
	ds_read_b64_tr_b16 v[86:87], v205 offset:0xa00
	v_mfma_f32_32x32x16_bf16 v[50:65], v[72:75], v[88:91], v[50:65]
	ds_read_b64_tr_b16 v[88:89], v205 offset:0x1200
	ds_read_b64_tr_b16 v[90:91], v205 offset:0x1a00
	v_mfma_f32_32x32x16_bf16 v[50:65], v[76:79], v[92:95], v[50:65]
	ds_read_b64_tr_b16 v[92:93], v205 offset:0x2200
	ds_read_b64_tr_b16 v[94:95], v205 offset:0x2a00
	ds_read_b64_tr_b16 v[158:159], v205 offset:0x3200
	ds_read_b64_tr_b16 v[160:161], v205 offset:0x3a00
	s_waitcnt lgkmcnt(0)
	v_mfma_f32_32x32x16_bf16 v[50:65], v[80:83], v[154:157], v[50:65]
	v_mfma_f32_32x32x16_bf16 v[34:49], v[68:71], v[84:87], v[34:49]
	ds_read_b64_tr_b16 v[84:85], v205 offset:0x400
	ds_read_b64_tr_b16 v[86:87], v205 offset:0xc00
	v_mfma_f32_32x32x16_bf16 v[34:49], v[72:75], v[88:91], v[34:49]
	ds_read_b64_tr_b16 v[88:89], v205 offset:0x1400
	ds_read_b64_tr_b16 v[90:91], v205 offset:0x1c00
	v_mfma_f32_32x32x16_bf16 v[34:49], v[76:79], v[92:95], v[34:49]
	ds_read_b64_tr_b16 v[92:93], v205 offset:0x2400
	ds_read_b64_tr_b16 v[94:95], v205 offset:0x2c00
	ds_read_b64_tr_b16 v[154:155], v205 offset:0x3400
	ds_read_b64_tr_b16 v[156:157], v205 offset:0x3c00
	s_waitcnt lgkmcnt(0)
	v_mfma_f32_32x32x16_bf16 v[34:49], v[80:83], v[158:161], v[34:49]
	v_mfma_f32_32x32x16_bf16 v[18:33], v[68:71], v[84:87], v[18:33]
	ds_read_b64_tr_b16 v[84:85], v205 offset:0x600
	ds_read_b64_tr_b16 v[86:87], v205 offset:0xe00
	v_mfma_f32_32x32x16_bf16 v[18:33], v[72:75], v[88:91], v[18:33]
	ds_read_b64_tr_b16 v[88:89], v205 offset:0x1600
	ds_read_b64_tr_b16 v[90:91], v205 offset:0x1e00
	v_mfma_f32_32x32x16_bf16 v[18:33], v[76:79], v[92:95], v[18:33]
	ds_read_b64_tr_b16 v[92:93], v205 offset:0x2600
	ds_read_b64_tr_b16 v[94:95], v205 offset:0x2e00
	ds_read_b64_tr_b16 v[158:159], v205 offset:0x3600
	ds_read_b64_tr_b16 v[160:161], v205 offset:0x3e00
	s_waitcnt lgkmcnt(0)
	v_mfma_f32_32x32x16_bf16 v[18:33], v[80:83], v[154:157], v[18:33]
	v_mfma_f32_32x32x16_bf16 v[2:17], v[68:71], v[84:87], v[2:17]
	v_mfma_f32_32x32x16_bf16 v[2:17], v[72:75], v[88:91], v[2:17]
	v_mfma_f32_32x32x16_bf16 v[2:17], v[76:79], v[92:95], v[2:17]
	v_mfma_f32_32x32x16_bf16 v[2:17], v[80:83], v[158:161], v[2:17]
